# rowss loads hoisted in both W_in and FFN2 gate/up epilogues, with the 2-wait-state pad before overwriting 128-bit store data (fixes the earlier race)
# baseline (speedup 1.0000x reference)
; __device__ __forceinline__ unsigned cvt_pk_bf16(float lo, float hi) { unsigned r; asm volatile("v_cvt_pk_bf16_f32 %0, %1, %2" : "=v"(r) : "v"(lo), "v"(hi)); return r; }
;     __device__ __forceinline__ void operator()(const f32x4 (&acc)[2][2][4][2], const Unit& u, int wr, int wc, int fr, int fq) const {
;     ...
;             for (int m = 0; m < 4; ++m) { const int row = row0 + ai * HALF + m * 16;
;                 const float rs = 1.0f / sqrtf(rowss[row] * (1.0f / 2048.0f) + 1e-6f);
; #pragma unroll
;                 for (int bj = 0; bj < 2; ++bj) { const f32x4 v0 = acc[ai][bj][m][0] * rs, v1 = acc[ai][bj][m][1] * rs;
;                     u32x4 w; w.x = cvt_pk_bf16(v0[0], v0[1]); w.y = cvt_pk_bf16(v0[2], v0[3]); w.z = cvt_pk_bf16(v1[0], v1[1]); w.w = cvt_pk_bf16(v1[2], v1[3]);
;                     const int cb = u.pn * BM + bj * HALF;
;                     bf16_t* dst;
;                     if (cb < 3072) dst = O + (size_t)row * ldc + cb + cw;
.LBB0_396:
	s_lshl_b32 s0, s0, 8
	s_add_i32 s5, s0, s54
	v_or_b32_e32 v148, s5, v139
	v_ashrrev_i32_e32 v149, 31, v148
	v_lshl_add_u64 v[150:151], v[148:149], 2, s[16:17]
	global_load_dword v136, v[150:151], off
	global_load_dword v199, v[150:151], off offset:64
	global_load_dword v200, v[150:151], off offset:128
	global_load_dword v201, v[150:151], off offset:192
	global_load_dword v202, v[150:151], off offset:512
	global_load_dword v203, v[150:151], off offset:576
	global_load_dword v204, v[150:151], off offset:640
	global_load_dword v205, v[150:151], off offset:704
	s_lshl_b32 s38, s4, 8
	v_lshlrev_b32_e32 v149, 7, v148
	s_add_i32 s0, s38, 0xfffff400
	v_and_b32_e32 v149, 0x7e780, v149
	s_lshr_b32 s0, s0, 10
	s_ashr_i32 s5, s5, 9
	s_lshl_b64 s[40:41], s[0:1], 25
	s_and_b32 s29, s5, -8
	s_cmp_gt_i32 s4, 11
	s_cselect_b64 s[10:11], -1, 0
	s_mov_b64 s[8:9], -1
	s_waitcnt vmcnt(7)
	v_fmamk_f32 v136, v136, 0x3a000000, v162
	s_nop 1
	v_rsq_f32_e32 v136, v136
	v_lshlrev_b32_e32 v152, 1, v149
	s_nop 1
	s_nop 0
	v_mov_b32_e32 v136, v136
	s_and_b64 s[4:5], exec, s[10:11]
	s_nop 0
	v_mov_b32_e32 v156, v136
	v_pk_mul_f32 v[164:165], v[122:123], v[156:157] op_sel_hi:[1,0]
	v_pk_mul_f32 v[122:123], v[120:121], v[156:157] op_sel_hi:[1,0]
	s_mov_b64 vcc, s[4:5]
	v_pk_mul_f32 v[126:127], v[126:127], v[156:157] op_sel_hi:[1,0]
	v_pk_mul_f32 v[124:125], v[124:125], v[156:157] op_sel_hi:[1,0]
	s_nop 0
	v_cvt_pk_bf16_f32 v120, v124, v125
	v_cvt_pk_bf16_f32 v121, v126, v127
	v_cvt_pk_bf16_f32 v122, v122, v123
	v_cvt_pk_bf16_f32 v123, v164, v165
	s_cbranch_vccz .LBB0_398
	s_lshr_b32 s0, s38, 7
	s_and_b32 s0, s0, 6
	s_add_u32 s8, s52, s40
	s_addc_u32 s9, s53, s41
	s_or_b32 s4, s29, s0
	s_ashr_i32 s5, s4, 31
	s_lshl_b64 s[4:5], s[4:5], 20
	s_add_u32 s4, s8, s4
	s_addc_u32 s5, s9, s5
	v_mov_b32_e32 v153, v137
	v_lshl_add_u64 v[154:155], s[4:5], 0, v[152:153]
	s_mov_b64 s[8:9], 0

; __device__ __forceinline__ unsigned cvt_pk_bf16(float lo, float hi) { unsigned r; asm volatile("v_cvt_pk_bf16_f32 %0, %1, %2" : "=v"(r) : "v"(lo), "v"(hi)); return r; }
;     __device__ __forceinline__ void operator()(const f32x4 (&acc)[2][2][4][2], const Unit& u, int wr, int wc, int fr, int fq) const {
;     ...
;             for (int m = 0; m < 4; ++m) { const int row = row0 + ai * HALF + m * 16;
;                 const float rs = 1.0f / sqrtf(rowss[row] * (1.0f / 2048.0f) + 1e-6f);
; #pragma unroll
;                 for (int bj = 0; bj < 2; ++bj) { const f32x4 v0 = acc[ai][bj][m][0] * rs, v1 = acc[ai][bj][m][1] * rs;
;                     u32x4 w; w.x = cvt_pk_bf16(v0[0], v0[1]); w.y = cvt_pk_bf16(v0[2], v0[3]); w.z = cvt_pk_bf16(v1[0], v1[1]); w.w = cvt_pk_bf16(v1[2], v1[3]);
;                     const int cb = u.pn * BM + bj * HALF;
;                     bf16_t* dst;
;                     if (cb < 3072) dst = O + (size_t)row * ldc + cb + cw;
;                     else { const int idx = (cb - 3072) >> 7, which = idx >> 3, head = idx & 7;
;                         dst = QKVC + (size_t)which * ((size_t)16384 * 1024) + ((size_t)((row >> 12) * 8 + head) * 4096 + (row & 4095)) * 128 + cw; }
;                     *(u32x4*)dst = w; } }
.LBB0_404:
	v_lshl_add_u64 v[116:117], v[116:117], 0, v[136:137]
	global_store_dwordx4 v[116:117], v[112:115], off
	s_mov_b64 s[44:45], -1
	s_nop 0
	v_or_b32_e32 v112, 16, v148
	v_ashrrev_i32_e32 v113, 31, v112
	v_lshl_add_u64 v[114:115], v[112:113], 2, s[16:17]
	s_waitcnt vmcnt(8)
	s_nop 1
	v_mov_b32_e32 v113, v199
	v_cndmask_b32_e64 v115, 0, 1, s[10:11]
	v_cmp_ne_u32_e64 s[8:9], 1, v115
	v_lshlrev_b32_e32 v116, 7, v112
	v_fmamk_f32 v113, v113, 0x3a000000, v162
	s_nop 1
	v_rsq_f32_e32 v113, v113
	v_and_b32_e32 v118, 0x7ef80, v116
	s_nop 0
	s_nop 1
	s_nop 0
	v_mov_b32_e32 v113, v113
	s_nop 0
	v_mov_b32_e32 v114, v113
	v_pk_mul_f32 v[108:109], v[108:109], v[114:115] op_sel_hi:[1,0]
	s_andn2_b64 vcc, exec, s[10:11]
	v_pk_mul_f32 v[110:111], v[110:111], v[114:115] op_sel_hi:[1,0]
	v_pk_mul_f32 v[116:117], v[106:107], v[114:115] op_sel_hi:[1,0]
	v_pk_mul_f32 v[106:107], v[104:105], v[114:115] op_sel_hi:[1,0]
	v_cvt_pk_bf16_f32 v104, v108, v109
	v_lshlrev_b32_e32 v108, 1, v118
	v_cvt_pk_bf16_f32 v105, v110, v111
	v_cvt_pk_bf16_f32 v106, v106, v107
	v_cvt_pk_bf16_f32 v107, v116, v117
	s_cbranch_vccnz .LBB0_406
	s_lshr_b32 s4, s38, 7
	s_and_b32 s4, s4, 6
	s_add_u32 s10, s52, s40
	s_addc_u32 s11, s53, s41
	s_or_b32 s4, s29, s4
	s_ashr_i32 s5, s4, 31
	s_lshl_b64 s[4:5], s[4:5], 20
	s_add_u32 s4, s10, s4
	s_addc_u32 s5, s11, s5
	v_mov_b32_e32 v109, v137
	v_lshl_add_u64 v[110:111], s[4:5], 0, v[108:109]
	s_mov_b64 s[44:45], 0

; __device__ __forceinline__ unsigned cvt_pk_bf16(float lo, float hi) { unsigned r; asm volatile("v_cvt_pk_bf16_f32 %0, %1, %2" : "=v"(r) : "v"(lo), "v"(hi)); return r; }
;     __device__ __forceinline__ void operator()(const f32x4 (&acc)[2][2][4][2], const Unit& u, int wr, int wc, int fr, int fq) const {
;     ...
;             for (int m = 0; m < 4; ++m) { const int row = row0 + ai * HALF + m * 16;
;                 const float rs = 1.0f / sqrtf(rowss[row] * (1.0f / 2048.0f) + 1e-6f);
; #pragma unroll
;                 for (int bj = 0; bj < 2; ++bj) { const f32x4 v0 = acc[ai][bj][m][0] * rs, v1 = acc[ai][bj][m][1] * rs;
;                     u32x4 w; w.x = cvt_pk_bf16(v0[0], v0[1]); w.y = cvt_pk_bf16(v0[2], v0[3]); w.z = cvt_pk_bf16(v1[0], v1[1]); w.w = cvt_pk_bf16(v1[2], v1[3]);
;                     const int cb = u.pn * BM + bj * HALF;
;                     bf16_t* dst;
;                     if (cb < 3072) dst = O + (size_t)row * ldc + cb + cw;
;                     else { const int idx = (cb - 3072) >> 7, which = idx >> 3, head = idx & 7;
;                         dst = QKVC + (size_t)which * ((size_t)16384 * 1024) + ((size_t)((row >> 12) * 8 + head) * 4096 + (row & 4095)) * 128 + cw; }
;                     *(u32x4*)dst = w; } }
.LBB0_412:
	v_lshl_add_u64 v[100:101], v[100:101], 0, v[136:137]
	global_store_dwordx4 v[100:101], v[96:99], off
	s_mov_b64 s[42:43], -1
	s_nop 0
	v_or_b32_e32 v96, 32, v148
	v_ashrrev_i32_e32 v97, 31, v96
	v_lshl_add_u64 v[98:99], v[96:97], 2, s[16:17]
	s_waitcnt vmcnt(9)
	s_nop 1
	v_mov_b32_e32 v97, v200
	v_lshlrev_b32_e32 v99, 7, v96
	v_and_b32_e32 v99, 0x7f780, v99
	v_fmamk_f32 v97, v97, 0x3a000000, v162
	s_nop 1
	v_rsq_f32_e32 v97, v97
	s_nop 1
	s_nop 0
	v_mov_b32_e32 v97, v97
	s_nop 0
	v_mov_b32_e32 v98, v97
	v_pk_mul_f32 v[92:93], v[92:93], v[98:99] op_sel_hi:[1,0]
	s_and_b64 vcc, exec, s[8:9]
	v_pk_mul_f32 v[94:95], v[94:95], v[98:99] op_sel_hi:[1,0]
	v_pk_mul_f32 v[100:101], v[90:91], v[98:99] op_sel_hi:[1,0]
	v_pk_mul_f32 v[90:91], v[88:89], v[98:99] op_sel_hi:[1,0]
	v_cvt_pk_bf16_f32 v88, v92, v93
	v_lshlrev_b32_e32 v92, 1, v99
	v_cvt_pk_bf16_f32 v89, v94, v95
	v_cvt_pk_bf16_f32 v90, v90, v91
	v_cvt_pk_bf16_f32 v91, v100, v101
	s_cbranch_vccnz .LBB0_414
	s_lshr_b32 s4, s38, 7
	s_and_b32 s4, s4, 6
	s_add_u32 s31, s52, s40
	s_addc_u32 s33, s53, s41
	s_or_b32 s4, s29, s4
	s_ashr_i32 s5, s4, 31
	s_lshl_b64 s[4:5], s[4:5], 20
	s_add_u32 s4, s31, s4
	s_addc_u32 s5, s33, s5
	v_mov_b32_e32 v93, v137
	v_lshl_add_u64 v[94:95], s[4:5], 0, v[92:93]
	s_mov_b64 s[42:43], 0

; __device__ __forceinline__ unsigned cvt_pk_bf16(float lo, float hi) { unsigned r; asm volatile("v_cvt_pk_bf16_f32 %0, %1, %2" : "=v"(r) : "v"(lo), "v"(hi)); return r; }
;     __device__ __forceinline__ void operator()(const f32x4 (&acc)[2][2][4][2], const Unit& u, int wr, int wc, int fr, int fq) const {
;     ...
;             for (int m = 0; m < 4; ++m) { const int row = row0 + ai * HALF + m * 16;
;                 const float rs = 1.0f / sqrtf(rowss[row] * (1.0f / 2048.0f) + 1e-6f);
; #pragma unroll
;                 for (int bj = 0; bj < 2; ++bj) { const f32x4 v0 = acc[ai][bj][m][0] * rs, v1 = acc[ai][bj][m][1] * rs;
;                     u32x4 w; w.x = cvt_pk_bf16(v0[0], v0[1]); w.y = cvt_pk_bf16(v0[2], v0[3]); w.z = cvt_pk_bf16(v1[0], v1[1]); w.w = cvt_pk_bf16(v1[2], v1[3]);
;                     const int cb = u.pn * BM + bj * HALF;
;                     bf16_t* dst;
;                     if (cb < 3072) dst = O + (size_t)row * ldc + cb + cw;
;                     else { const int idx = (cb - 3072) >> 7, which = idx >> 3, head = idx & 7;
;                         dst = QKVC + (size_t)which * ((size_t)16384 * 1024) + ((size_t)((row >> 12) * 8 + head) * 4096 + (row & 4095)) * 128 + cw; }
;                     *(u32x4*)dst = w; } }
.LBB0_420:
	v_lshl_add_u64 v[84:85], v[84:85], 0, v[136:137]
	global_store_dwordx4 v[84:85], v[80:83], off
	s_mov_b64 s[42:43], -1
	s_nop 0
	v_or_b32_e32 v80, 48, v148
	v_ashrrev_i32_e32 v81, 31, v80
	v_lshl_add_u64 v[82:83], v[80:81], 2, s[16:17]
	s_waitcnt vmcnt(10)
	s_nop 1
	v_mov_b32_e32 v81, v201
	v_lshlrev_b32_e32 v83, 7, v80
	v_and_b32_e32 v83, 0x7ff80, v83
	v_fmamk_f32 v81, v81, 0x3a000000, v162
	s_nop 1
	v_rsq_f32_e32 v81, v81
	s_nop 1
	s_nop 0
	v_mov_b32_e32 v81, v81
	s_nop 0
	v_mov_b32_e32 v82, v81
	v_pk_mul_f32 v[76:77], v[76:77], v[82:83] op_sel_hi:[1,0]
	s_and_b64 vcc, exec, s[8:9]
	v_pk_mul_f32 v[78:79], v[78:79], v[82:83] op_sel_hi:[1,0]
	v_pk_mul_f32 v[84:85], v[74:75], v[82:83] op_sel_hi:[1,0]
	v_pk_mul_f32 v[74:75], v[72:73], v[82:83] op_sel_hi:[1,0]
	v_cvt_pk_bf16_f32 v72, v76, v77
	v_lshlrev_b32_e32 v76, 1, v83
	v_cvt_pk_bf16_f32 v73, v78, v79
	v_cvt_pk_bf16_f32 v74, v74, v75
	v_cvt_pk_bf16_f32 v75, v84, v85
	s_cbranch_vccnz .LBB0_422
	s_lshr_b32 s4, s38, 7
	s_and_b32 s4, s4, 6
	s_add_u32 s31, s52, s40
	s_addc_u32 s33, s53, s41
	s_or_b32 s4, s29, s4
	s_ashr_i32 s5, s4, 31
	s_lshl_b64 s[4:5], s[4:5], 20
	s_add_u32 s4, s31, s4
	s_addc_u32 s5, s33, s5
	v_mov_b32_e32 v77, v137
	v_lshl_add_u64 v[78:79], s[4:5], 0, v[76:77]
	s_mov_b64 s[42:43], 0

; __device__ __forceinline__ unsigned cvt_pk_bf16(float lo, float hi) { unsigned r; asm volatile("v_cvt_pk_bf16_f32 %0, %1, %2" : "=v"(r) : "v"(lo), "v"(hi)); return r; }
;     __device__ __forceinline__ void operator()(const f32x4 (&acc)[2][2][4][2], const Unit& u, int wr, int wc, int fr, int fq) const {
;     ...
;             for (int m = 0; m < 4; ++m) { const int row = row0 + ai * HALF + m * 16;
;                 const float rs = 1.0f / sqrtf(rowss[row] * (1.0f / 2048.0f) + 1e-6f);
; #pragma unroll
;                 for (int bj = 0; bj < 2; ++bj) { const f32x4 v0 = acc[ai][bj][m][0] * rs, v1 = acc[ai][bj][m][1] * rs;
;                     u32x4 w; w.x = cvt_pk_bf16(v0[0], v0[1]); w.y = cvt_pk_bf16(v0[2], v0[3]); w.z = cvt_pk_bf16(v1[0], v1[1]); w.w = cvt_pk_bf16(v1[2], v1[3]);
;                     const int cb = u.pn * BM + bj * HALF;
;                     bf16_t* dst;
;                     if (cb < 3072) dst = O + (size_t)row * ldc + cb + cw;
;                     else { const int idx = (cb - 3072) >> 7, which = idx >> 3, head = idx & 7;
;                         dst = QKVC + (size_t)which * ((size_t)16384 * 1024) + ((size_t)((row >> 12) * 8 + head) * 4096 + (row & 4095)) * 128 + cw; }
;                     *(u32x4*)dst = w; } }
.LBB0_428:
	v_lshl_add_u64 v[68:69], v[68:69], 0, v[136:137]
	global_store_dwordx4 v[68:69], v[64:67], off
	s_waitcnt vmcnt(11)
	s_nop 1
	v_mov_b32_e32 v64, v202
	s_mov_b64 s[42:43], -1
	v_add_u32_e32 v67, 0x80, v148
	v_lshlrev_b32_e32 v68, 7, v67
	v_ashrrev_i32_e32 v66, 9, v67
	v_and_b32_e32 v66, -8, v66
	v_fmamk_f32 v64, v64, 0x3a000000, v162
	s_nop 1
	v_rsq_f32_e32 v64, v64
	v_and_b32_e32 v70, 0x7e780, v68
	s_nop 0
	s_nop 0
	v_mov_b32_e32 v64, v64
	s_nop 0
	v_mov_b32_e32 v64, v64
	v_pk_mul_f32 v[60:61], v[60:61], v[64:65] op_sel_hi:[1,0]
	s_and_b64 vcc, exec, s[8:9]
	v_pk_mul_f32 v[62:63], v[62:63], v[64:65] op_sel_hi:[1,0]
	v_pk_mul_f32 v[68:69], v[58:59], v[64:65] op_sel_hi:[1,0]
	v_pk_mul_f32 v[58:59], v[56:57], v[64:65] op_sel_hi:[1,0]
	v_cvt_pk_bf16_f32 v56, v60, v61
	v_lshlrev_b32_e32 v60, 1, v70
	v_cvt_pk_bf16_f32 v57, v62, v63
	v_cvt_pk_bf16_f32 v58, v58, v59
	v_cvt_pk_bf16_f32 v59, v68, v69
	s_cbranch_vccnz .LBB0_430
	s_lshr_b32 s29, s38, 7
	v_and_or_b32 v62, s29, 6, v66
	s_add_u32 s4, s52, s40
	v_ashrrev_i32_e32 v63, 31, v62
	s_addc_u32 s5, s53, s41
	v_lshlrev_b64 v[62:63], 20, v[62:63]
	v_lshl_add_u64 v[62:63], s[4:5], 0, v[62:63]
	v_mov_b32_e32 v61, v137
	v_lshl_add_u64 v[62:63], v[62:63], 0, v[60:61]
	s_mov_b64 s[42:43], 0

; __device__ __forceinline__ unsigned cvt_pk_bf16(float lo, float hi) { unsigned r; asm volatile("v_cvt_pk_bf16_f32 %0, %1, %2" : "=v"(r) : "v"(lo), "v"(hi)); return r; }
;     __device__ __forceinline__ void operator()(const f32x4 (&acc)[2][2][4][2], const Unit& u, int wr, int wc, int fr, int fq) const {
;     ...
;             for (int m = 0; m < 4; ++m) { const int row = row0 + ai * HALF + m * 16;
;                 const float rs = 1.0f / sqrtf(rowss[row] * (1.0f / 2048.0f) + 1e-6f);
; #pragma unroll
;                 for (int bj = 0; bj < 2; ++bj) { const f32x4 v0 = acc[ai][bj][m][0] * rs, v1 = acc[ai][bj][m][1] * rs;
;                     u32x4 w; w.x = cvt_pk_bf16(v0[0], v0[1]); w.y = cvt_pk_bf16(v0[2], v0[3]); w.z = cvt_pk_bf16(v1[0], v1[1]); w.w = cvt_pk_bf16(v1[2], v1[3]);
;                     const int cb = u.pn * BM + bj * HALF;
;                     bf16_t* dst;
;                     if (cb < 3072) dst = O + (size_t)row * ldc + cb + cw;
;                     else { const int idx = (cb - 3072) >> 7, which = idx >> 3, head = idx & 7;
;                         dst = QKVC + (size_t)which * ((size_t)16384 * 1024) + ((size_t)((row >> 12) * 8 + head) * 4096 + (row & 4095)) * 128 + cw; }
;                     *(u32x4*)dst = w; } }
.LBB0_436:
	v_lshl_add_u64 v[52:53], v[52:53], 0, v[136:137]
	global_store_dwordx4 v[52:53], v[48:51], off
	s_waitcnt vmcnt(12)
	s_nop 1
	v_mov_b32_e32 v48, v203
	s_mov_b64 s[42:43], -1
	v_add_u32_e32 v50, 0x90, v148
	v_lshlrev_b32_e32 v51, 7, v50
	v_and_b32_e32 v51, 0x7ef80, v51
	v_fmamk_f32 v48, v48, 0x3a000000, v162
	s_nop 1
	v_rsq_f32_e32 v48, v48
	s_nop 1
	s_nop 0
	v_mov_b32_e32 v48, v48
	s_nop 0
	v_mov_b32_e32 v48, v48
	v_pk_mul_f32 v[44:45], v[44:45], v[48:49] op_sel_hi:[1,0]
	s_and_b64 vcc, exec, s[8:9]
	v_pk_mul_f32 v[46:47], v[46:47], v[48:49] op_sel_hi:[1,0]
	v_pk_mul_f32 v[52:53], v[42:43], v[48:49] op_sel_hi:[1,0]
	v_pk_mul_f32 v[42:43], v[40:41], v[48:49] op_sel_hi:[1,0]
	v_cvt_pk_bf16_f32 v40, v44, v45
	v_lshlrev_b32_e32 v44, 1, v51
	v_cvt_pk_bf16_f32 v41, v46, v47
	v_cvt_pk_bf16_f32 v42, v42, v43
	v_cvt_pk_bf16_f32 v43, v52, v53
	s_cbranch_vccnz .LBB0_438
	s_lshr_b32 s29, s38, 7
	v_and_or_b32 v46, s29, 6, v66
	s_add_u32 s4, s52, s40
	v_ashrrev_i32_e32 v47, 31, v46
	s_addc_u32 s5, s53, s41
	v_lshlrev_b64 v[46:47], 20, v[46:47]
	v_lshl_add_u64 v[46:47], s[4:5], 0, v[46:47]
	v_mov_b32_e32 v45, v137
	v_lshl_add_u64 v[46:47], v[46:47], 0, v[44:45]
	s_mov_b64 s[42:43], 0

; __device__ __forceinline__ unsigned cvt_pk_bf16(float lo, float hi) { unsigned r; asm volatile("v_cvt_pk_bf16_f32 %0, %1, %2" : "=v"(r) : "v"(lo), "v"(hi)); return r; }
;     __device__ __forceinline__ void operator()(const f32x4 (&acc)[2][2][4][2], const Unit& u, int wr, int wc, int fr, int fq) const {
;     ...
;             for (int m = 0; m < 4; ++m) { const int row = row0 + ai * HALF + m * 16;
;                 const float rs = 1.0f / sqrtf(rowss[row] * (1.0f / 2048.0f) + 1e-6f);
; #pragma unroll
;                 for (int bj = 0; bj < 2; ++bj) { const f32x4 v0 = acc[ai][bj][m][0] * rs, v1 = acc[ai][bj][m][1] * rs;
;                     u32x4 w; w.x = cvt_pk_bf16(v0[0], v0[1]); w.y = cvt_pk_bf16(v0[2], v0[3]); w.z = cvt_pk_bf16(v1[0], v1[1]); w.w = cvt_pk_bf16(v1[2], v1[3]);
;                     const int cb = u.pn * BM + bj * HALF;
;                     bf16_t* dst;
;                     if (cb < 3072) dst = O + (size_t)row * ldc + cb + cw;
;                     else { const int idx = (cb - 3072) >> 7, which = idx >> 3, head = idx & 7;
;                         dst = QKVC + (size_t)which * ((size_t)16384 * 1024) + ((size_t)((row >> 12) * 8 + head) * 4096 + (row & 4095)) * 128 + cw; }
;                     *(u32x4*)dst = w; } }
.LBB0_444:
	v_lshl_add_u64 v[36:37], v[36:37], 0, v[136:137]
	global_store_dwordx4 v[36:37], v[32:35], off
	s_waitcnt vmcnt(13)
	s_nop 1
	v_mov_b32_e32 v32, v204
	s_mov_b64 s[42:43], -1
	v_add_u32_e32 v34, 0xa0, v148
	v_lshlrev_b32_e32 v35, 7, v34
	v_and_b32_e32 v35, 0x7f780, v35
	v_fmamk_f32 v32, v32, 0x3a000000, v162
	s_nop 1
	v_rsq_f32_e32 v32, v32
	s_nop 1
	s_nop 0
	v_mov_b32_e32 v32, v32
	s_nop 0
	v_mov_b32_e32 v32, v32
	v_pk_mul_f32 v[28:29], v[28:29], v[32:33] op_sel_hi:[1,0]
	s_and_b64 vcc, exec, s[8:9]
	v_pk_mul_f32 v[30:31], v[30:31], v[32:33] op_sel_hi:[1,0]
	v_pk_mul_f32 v[36:37], v[26:27], v[32:33] op_sel_hi:[1,0]
	v_pk_mul_f32 v[26:27], v[24:25], v[32:33] op_sel_hi:[1,0]
	v_cvt_pk_bf16_f32 v24, v28, v29
	v_lshlrev_b32_e32 v28, 1, v35
	v_cvt_pk_bf16_f32 v25, v30, v31
	v_cvt_pk_bf16_f32 v26, v26, v27
	v_cvt_pk_bf16_f32 v27, v36, v37
	s_cbranch_vccnz .LBB0_446
	s_lshr_b32 s29, s38, 7
	v_and_or_b32 v30, s29, 6, v66
	s_add_u32 s4, s52, s40
	v_ashrrev_i32_e32 v31, 31, v30
	s_addc_u32 s5, s53, s41
	v_lshlrev_b64 v[30:31], 20, v[30:31]
	v_lshl_add_u64 v[30:31], s[4:5], 0, v[30:31]
	v_mov_b32_e32 v29, v137
	v_lshl_add_u64 v[30:31], v[30:31], 0, v[28:29]
	s_mov_b64 s[42:43], 0

; __device__ __forceinline__ unsigned cvt_pk_bf16(float lo, float hi) { unsigned r; asm volatile("v_cvt_pk_bf16_f32 %0, %1, %2" : "=v"(r) : "v"(lo), "v"(hi)); return r; }
;     __device__ __forceinline__ void operator()(const f32x4 (&acc)[2][2][4][2], const Unit& u, int wr, int wc, int fr, int fq) const {
;     ...
;             for (int m = 0; m < 4; ++m) { const int row = row0 + ai * HALF + m * 16;
;                 const float rs = 1.0f / sqrtf(rowss[row] * (1.0f / 2048.0f) + 1e-6f);
; #pragma unroll
;                 for (int bj = 0; bj < 2; ++bj) { const f32x4 v0 = acc[ai][bj][m][0] * rs, v1 = acc[ai][bj][m][1] * rs;
;                     u32x4 w; w.x = cvt_pk_bf16(v0[0], v0[1]); w.y = cvt_pk_bf16(v0[2], v0[3]); w.z = cvt_pk_bf16(v1[0], v1[1]); w.w = cvt_pk_bf16(v1[2], v1[3]);
;                     const int cb = u.pn * BM + bj * HALF;
;                     bf16_t* dst;
;                     if (cb < 3072) dst = O + (size_t)row * ldc + cb + cw;
;                     else { const int idx = (cb - 3072) >> 7, which = idx >> 3, head = idx & 7;
;                         dst = QKVC + (size_t)which * ((size_t)16384 * 1024) + ((size_t)((row >> 12) * 8 + head) * 4096 + (row & 4095)) * 128 + cw; }
;                     *(u32x4*)dst = w; } }
.LBB0_452:
	v_lshl_add_u64 v[20:21], v[20:21], 0, v[136:137]
	global_store_dwordx4 v[20:21], v[16:19], off
	s_waitcnt vmcnt(14)
	s_nop 1
	v_mov_b32_e32 v16, v205
	s_mov_b64 s[42:43], -1
	v_add_u32_e32 v18, 0xb0, v148
	v_lshlrev_b32_e32 v19, 7, v18
	v_and_b32_e32 v19, 0x7ff80, v19
	v_fmamk_f32 v16, v16, 0x3a000000, v162
	s_nop 1
	v_rsq_f32_e32 v16, v16
	s_nop 1
	s_nop 0
	v_mov_b32_e32 v16, v16
	s_nop 0
	v_mov_b32_e32 v16, v16
	v_pk_mul_f32 v[12:13], v[12:13], v[16:17] op_sel_hi:[1,0]
	s_and_b64 vcc, exec, s[8:9]
	v_pk_mul_f32 v[14:15], v[14:15], v[16:17] op_sel_hi:[1,0]
	v_pk_mul_f32 v[20:21], v[10:11], v[16:17] op_sel_hi:[1,0]
	v_pk_mul_f32 v[10:11], v[8:9], v[16:17] op_sel_hi:[1,0]
	v_cvt_pk_bf16_f32 v8, v12, v13
	v_lshlrev_b32_e32 v12, 1, v19
	v_cvt_pk_bf16_f32 v9, v14, v15
	v_cvt_pk_bf16_f32 v10, v10, v11
	v_cvt_pk_bf16_f32 v11, v20, v21
	s_cbranch_vccnz .LBB0_454
	s_lshr_b32 s8, s38, 7
	v_and_or_b32 v14, s8, 6, v66
	s_add_u32 s4, s52, s40
	v_ashrrev_i32_e32 v15, 31, v14
	s_addc_u32 s5, s53, s41
	v_lshlrev_b64 v[14:15], 20, v[14:15]
	v_lshl_add_u64 v[14:15], s[4:5], 0, v[14:15]
	v_mov_b32_e32 v13, v137
	v_lshl_add_u64 v[14:15], v[14:15], 0, v[12:13]
	s_mov_b64 s[42:43], 0

; __device__ __forceinline__ unsigned cvt_pk_bf16(float lo, float hi) { unsigned r; asm volatile("v_cvt_pk_bf16_f32 %0, %1, %2" : "=v"(r) : "v"(lo), "v"(hi)); return r; }
; __device__ __forceinline__ float silu_f(float g) { return g * __builtin_amdgcn_rcpf(1.0f + __builtin_amdgcn_exp2f(-1.44269504089f * g)); }
;     __device__ __forceinline__ void operator()(const f32x4 (&acc)[2][2][4][2], const Unit& u, int wr, int wc, int fr, int fq) const {
;     ...
;             for (int m = 0; m < 4; ++m) { bf16_t* rowp = O + (size_t)(row0 + ai * HALF + m * 16) * ldc + col0;
;                 const float rs = rowss ? 1.0f / sqrtf(rowss[row0 + ai * HALF + m * 16] * (1.0f / 2048.0f) + 1e-6f) : 1.0f;
;                 const f32x4 g0 = acc[ai][0][m][0] * rs, g1 = acc[ai][0][m][1] * rs, u0 = acc[ai][1][m][0] * rs, u1 = acc[ai][1][m][1] * rs;
;                 float h[8];
; #pragma unroll
;                 for (int j = 0; j < 4; ++j) { h[j] = silu_f(g0[j]) * u0[j]; h[4 + j] = silu_f(g1[j]) * u1[j]; }
;                 u32x4 w; w.x = cvt_pk_bf16(h[0], h[1]); w.y = cvt_pk_bf16(h[2], h[3]); w.z = cvt_pk_bf16(h[4], h[5]); w.w = cvt_pk_bf16(h[6], h[7]);
;                 *(u32x4*)rowp = w; }
.LBB0_932:
	v_lshl_add_u32 v144, s4, 8, v150
	v_ashrrev_i32_e32 v145, 31, v144
	v_lshl_add_u64 v[148:149], v[144:145], 2, s[10:11]
	global_load_dword v145, v[148:149], off
	global_load_dword v199, v[148:149], off offset:64
	global_load_dword v200, v[148:149], off offset:128
	global_load_dword v201, v[148:149], off offset:192
	global_load_dword v202, v[148:149], off offset:512
	global_load_dword v203, v[148:149], off offset:576
	global_load_dword v204, v[148:149], off offset:640
	global_load_dword v205, v[148:149], off offset:704
	v_mov_b32_e32 v162, v120
	v_mov_b32_e32 v163, v112
	v_mov_b32_e32 v112, v121
	v_lshl_or_b32 v158, s5, 7, v152
	v_ashrrev_i32_e32 v159, 31, v158
	v_mov_b64_e32 v[146:147], s[74:75]
	v_mov_b32_e32 v164, v122
	v_mov_b32_e32 v165, v114
	v_mov_b32_e32 v114, v123
	v_mad_i64_i32 v[122:123], s[4:5], v144, s43, v[146:147]
	v_mov_b32_e32 v160, v124
	v_mov_b32_e32 v124, v126
	v_or_b32_e32 v126, 16, v144
	v_mov_b32_e32 v161, v116
	v_mov_b32_e32 v116, v125
	v_mov_b32_e32 v125, v118
	v_mov_b32_e32 v118, v127
	v_ashrrev_i32_e32 v127, 31, v126
	s_waitcnt vmcnt(7)
	v_fmamk_f32 v120, v145, 0x3a000000, v156
	s_nop 1
	v_rsq_f32_e32 v145, v120
	v_lshlrev_b64 v[120:121], 1, v[158:159]
	v_lshl_add_u64 v[122:123], v[122:123], 0, v[120:121]
	s_nop 1
	s_nop 0
	v_mov_b32_e32 v145, v145
	v_lshl_add_u64 v[158:159], v[126:127], 2, s[10:11]
	s_nop 0
	v_mov_b32_e32 v166, v145
	v_pk_mul_f32 v[116:117], v[116:117], v[166:167] op_sel_hi:[1,0]
	v_pk_mul_f32 v[112:113], v[112:113], v[166:167] op_sel_hi:[1,0]
	v_pk_mul_f32 v[124:125], v[124:125], v[166:167] op_sel_hi:[1,0]
	v_pk_mul_f32 v[114:115], v[114:115], v[166:167] op_sel_hi:[1,0]
	v_pk_mul_f32 v[160:161], v[160:161], v[166:167] op_sel_hi:[1,0]
	v_pk_mul_f32 v[162:163], v[162:163], v[166:167] op_sel_hi:[1,0]
	v_pk_mul_f32 v[164:165], v[164:165], v[166:167] op_sel_hi:[1,0]
	v_pk_mul_f32 v[118:119], v[118:119], v[166:167] op_sel_hi:[1,0]
	v_mul_f32_e32 v166, 0xbfb8aa3b, v117
	v_mul_f32_e32 v167, 0xbfb8aa3b, v113
	v_mul_f32_e32 v168, 0xbfb8aa3b, v125
	v_mul_f32_e32 v171, 0xbfb8aa3b, v115
	v_mul_f32_e32 v127, 0xbfb8aa3b, v161
	v_mul_f32_e32 v145, 0xbfb8aa3b, v163
	v_mul_f32_e32 v169, 0xbfb8aa3b, v165
	v_mul_f32_e32 v170, 0xbfb8aa3b, v119
	v_exp_f32_e32 v166, v166
	v_exp_f32_e32 v167, v167
	v_exp_f32_e32 v168, v168
	v_exp_f32_e32 v171, v171
	v_exp_f32_e32 v127, v127
	v_exp_f32_e32 v145, v145
	v_exp_f32_e32 v169, v169
	v_exp_f32_e32 v170, v170
	v_add_f32_e32 v166, 1.0, v166
	v_add_f32_e32 v167, 1.0, v167
	v_add_f32_e32 v168, 1.0, v168
	v_add_f32_e32 v171, 1.0, v171
	v_add_f32_e32 v127, 1.0, v127
	v_add_f32_e32 v145, 1.0, v145
	v_add_f32_e32 v169, 1.0, v169
	v_add_f32_e32 v170, 1.0, v170
	v_rcp_f32_e32 v166, v166
	v_rcp_f32_e32 v167, v167
	v_rcp_f32_e32 v168, v168
	v_rcp_f32_e32 v171, v171
	v_rcp_f32_e32 v127, v127
	v_rcp_f32_e32 v145, v145
	v_rcp_f32_e32 v169, v169
	v_rcp_f32_e32 v170, v170
	v_mul_f32_e32 v117, v117, v166
	v_mul_f32_e32 v113, v113, v167
	v_mul_f32_e32 v125, v125, v168
	v_mul_f32_e32 v115, v115, v171
	v_mul_f32_e32 v127, v161, v127
	v_mul_f32_e32 v145, v163, v145
	v_mul_f32_e32 v161, v165, v169
	v_mul_f32_e32 v119, v119, v170
	v_mul_f32_e32 v116, v116, v117
	v_mul_f32_e32 v117, v112, v113
	v_mul_f32_e32 v113, v124, v125
	v_mul_f32_e32 v115, v114, v115
	v_mul_f32_e32 v127, v160, v127
	v_mul_f32_e32 v145, v162, v145
	v_mul_f32_e32 v124, v164, v161
	v_mul_f32_e32 v118, v118, v119
	v_cvt_pk_bf16_f32 v112, v127, v116
	v_cvt_pk_bf16_f32 v113, v113, v118
	v_cvt_pk_bf16_f32 v114, v145, v117
	v_cvt_pk_bf16_f32 v115, v124, v115
	global_store_dwordx4 v[122:123], v[112:115], off
	s_waitcnt vmcnt(7)
	s_nop 1
	v_mov_b32_e32 v116, v199
	s_nop 0
	v_mov_b32_e32 v113, v100
	v_mov_b32_e32 v100, v109
	v_mov_b32_e32 v109, v98
	v_mov_b32_e32 v98, v107
	v_mov_b32_e32 v114, v104
	v_mov_b32_e32 v104, v110
	v_mov_b32_e32 v115, v96
	v_mov_b32_e32 v96, v105
	v_mov_b32_e32 v105, v102
	v_mov_b32_e32 v102, v111
	v_mov_b32_e32 v112, v108
	v_mov_b32_e32 v108, v106
	v_or_b32_e32 v106, 32, v144
	v_fmamk_f32 v107, v116, 0x3a000000, v156
	s_nop 1
	v_rsq_f32_e32 v116, v107
	v_mad_i64_i32 v[110:111], s[4:5], v126, s43, v[146:147]
	v_ashrrev_i32_e32 v107, 31, v106
	v_lshl_add_u64 v[110:111], v[110:111], 0, v[120:121]
	s_nop 0
	s_nop 1
	s_nop 0
	v_mov_b32_e32 v118, v116
	v_lshl_add_u64 v[116:117], v[106:107], 2, s[10:11]
	s_nop 0
	v_mov_b32_e32 v118, v118
	v_pk_mul_f32 v[100:101], v[100:101], v[118:119] op_sel_hi:[1,0]
	v_pk_mul_f32 v[96:97], v[96:97], v[118:119] op_sel_hi:[1,0]
	v_pk_mul_f32 v[104:105], v[104:105], v[118:119] op_sel_hi:[1,0]
	v_pk_mul_f32 v[98:99], v[98:99], v[118:119] op_sel_hi:[1,0]
	v_pk_mul_f32 v[112:113], v[112:113], v[118:119] op_sel_hi:[1,0]
	v_pk_mul_f32 v[114:115], v[114:115], v[118:119] op_sel_hi:[1,0]
	v_pk_mul_f32 v[108:109], v[108:109], v[118:119] op_sel_hi:[1,0]
	v_pk_mul_f32 v[102:103], v[102:103], v[118:119] op_sel_hi:[1,0]
	v_mul_f32_e32 v119, 0xbfb8aa3b, v101
	v_mul_f32_e32 v122, 0xbfb8aa3b, v97
	v_mul_f32_e32 v123, 0xbfb8aa3b, v105
	v_mul_f32_e32 v126, 0xbfb8aa3b, v99
	v_mul_f32_e32 v107, 0xbfb8aa3b, v113
	v_mul_f32_e32 v118, 0xbfb8aa3b, v115
	v_mul_f32_e32 v124, 0xbfb8aa3b, v109
	v_mul_f32_e32 v125, 0xbfb8aa3b, v103
	v_exp_f32_e32 v119, v119
	v_exp_f32_e32 v122, v122
	v_exp_f32_e32 v123, v123
	v_exp_f32_e32 v126, v126
	v_exp_f32_e32 v107, v107
	v_exp_f32_e32 v118, v118
	v_exp_f32_e32 v124, v124
	v_exp_f32_e32 v125, v125
	v_add_f32_e32 v119, 1.0, v119
	v_add_f32_e32 v122, 1.0, v122
	v_add_f32_e32 v123, 1.0, v123
	v_add_f32_e32 v126, 1.0, v126
	v_add_f32_e32 v107, 1.0, v107
	v_add_f32_e32 v118, 1.0, v118
	v_add_f32_e32 v124, 1.0, v124
	v_add_f32_e32 v125, 1.0, v125
	v_rcp_f32_e32 v119, v119
	v_rcp_f32_e32 v122, v122
	v_rcp_f32_e32 v123, v123
	v_rcp_f32_e32 v126, v126
	v_rcp_f32_e32 v107, v107
	v_rcp_f32_e32 v118, v118
	v_rcp_f32_e32 v124, v124
	v_rcp_f32_e32 v125, v125
	v_mul_f32_e32 v101, v101, v119
	v_mul_f32_e32 v97, v97, v122
	v_mul_f32_e32 v105, v105, v123
	v_mul_f32_e32 v99, v99, v126
	v_mul_f32_e32 v107, v113, v107
	v_mul_f32_e32 v113, v115, v118
	v_mul_f32_e32 v109, v109, v124
	v_mul_f32_e32 v103, v103, v125
	v_mul_f32_e32 v100, v100, v101
	v_mul_f32_e32 v101, v96, v97
	v_mul_f32_e32 v97, v104, v105
	v_mul_f32_e32 v99, v98, v99
	v_mul_f32_e32 v107, v112, v107
	v_mul_f32_e32 v112, v114, v113
	v_mul_f32_e32 v104, v108, v109
	v_mul_f32_e32 v102, v102, v103
	v_cvt_pk_bf16_f32 v96, v107, v100
	v_cvt_pk_bf16_f32 v97, v97, v102
	v_cvt_pk_bf16_f32 v98, v112, v101
	v_cvt_pk_bf16_f32 v99, v104, v99
	global_store_dwordx4 v[110:111], v[96:99], off
	s_waitcnt vmcnt(7)
; __device__ __forceinline__ unsigned cvt_pk_bf16(float lo, float hi) { unsigned r; asm volatile("v_cvt_pk_bf16_f32 %0, %1, %2" : "=v"(r) : "v"(lo), "v"(hi)); return r; }
; __device__ __forceinline__ float silu_f(float g) { return g * __builtin_amdgcn_rcpf(1.0f + __builtin_amdgcn_exp2f(-1.44269504089f * g)); }
;     __device__ __forceinline__ void operator()(const f32x4 (&acc)[2][2][4][2], const Unit& u, int wr, int wc, int fr, int fq) const {
;     ...
;             for (int m = 0; m < 4; ++m) { bf16_t* rowp = O + (size_t)(row0 + ai * HALF + m * 16) * ldc + col0;
;                 const float rs = rowss ? 1.0f / sqrtf(rowss[row0 + ai * HALF + m * 16] * (1.0f / 2048.0f) + 1e-6f) : 1.0f;
;                 const f32x4 g0 = acc[ai][0][m][0] * rs, g1 = acc[ai][0][m][1] * rs, u0 = acc[ai][1][m][0] * rs, u1 = acc[ai][1][m][1] * rs;
;                 float h[8];
; #pragma unroll
;                 for (int j = 0; j < 4; ++j) { h[j] = silu_f(g0[j]) * u0[j]; h[4 + j] = silu_f(g1[j]) * u1[j]; }
;                 u32x4 w; w.x = cvt_pk_bf16(h[0], h[1]); w.y = cvt_pk_bf16(h[2], h[3]); w.z = cvt_pk_bf16(h[4], h[5]); w.w = cvt_pk_bf16(h[6], h[7]);
;                 *(u32x4*)rowp = w; }
	s_nop 1
	v_mov_b32_e32 v100, v200
	s_nop 0
	v_mov_b32_e32 v97, v84
	v_mov_b32_e32 v84, v93
	v_mov_b32_e32 v93, v82
	v_mov_b32_e32 v82, v91
	v_mov_b32_e32 v98, v88
	v_mov_b32_e32 v88, v94
	v_mov_b32_e32 v99, v80
	v_mov_b32_e32 v80, v89
	v_mov_b32_e32 v89, v86
	v_mov_b32_e32 v86, v95
	v_mov_b32_e32 v96, v92
	v_mov_b32_e32 v92, v90
	v_or_b32_e32 v90, 48, v144
	v_fmamk_f32 v91, v100, 0x3a000000, v156
	s_nop 1
	v_rsq_f32_e32 v100, v91
	v_mad_i64_i32 v[94:95], s[4:5], v106, s43, v[146:147]
	v_ashrrev_i32_e32 v91, 31, v90
	v_lshl_add_u64 v[94:95], v[94:95], 0, v[120:121]
	s_nop 0
	s_nop 1
	s_nop 0
	v_mov_b32_e32 v102, v100
	v_lshl_add_u64 v[100:101], v[90:91], 2, s[10:11]
	s_nop 0
	v_mov_b32_e32 v102, v102
	v_pk_mul_f32 v[84:85], v[84:85], v[102:103] op_sel_hi:[1,0]
	v_pk_mul_f32 v[80:81], v[80:81], v[102:103] op_sel_hi:[1,0]
	v_pk_mul_f32 v[88:89], v[88:89], v[102:103] op_sel_hi:[1,0]
	v_pk_mul_f32 v[82:83], v[82:83], v[102:103] op_sel_hi:[1,0]
	v_pk_mul_f32 v[96:97], v[96:97], v[102:103] op_sel_hi:[1,0]
	v_pk_mul_f32 v[98:99], v[98:99], v[102:103] op_sel_hi:[1,0]
	v_pk_mul_f32 v[92:93], v[92:93], v[102:103] op_sel_hi:[1,0]
	v_pk_mul_f32 v[86:87], v[86:87], v[102:103] op_sel_hi:[1,0]
	v_mul_f32_e32 v103, 0xbfb8aa3b, v85
	v_mul_f32_e32 v104, 0xbfb8aa3b, v81
	v_mul_f32_e32 v105, 0xbfb8aa3b, v89
	v_mul_f32_e32 v108, 0xbfb8aa3b, v83
	v_mul_f32_e32 v91, 0xbfb8aa3b, v97
	v_mul_f32_e32 v102, 0xbfb8aa3b, v99
	v_mul_f32_e32 v106, 0xbfb8aa3b, v93
	v_mul_f32_e32 v107, 0xbfb8aa3b, v87
	v_exp_f32_e32 v103, v103
	v_exp_f32_e32 v104, v104
	v_exp_f32_e32 v105, v105
	v_exp_f32_e32 v108, v108
	v_exp_f32_e32 v91, v91
	v_exp_f32_e32 v102, v102
	v_exp_f32_e32 v106, v106
	v_exp_f32_e32 v107, v107
	v_add_f32_e32 v103, 1.0, v103
	v_add_f32_e32 v104, 1.0, v104
	v_add_f32_e32 v105, 1.0, v105
	v_add_f32_e32 v108, 1.0, v108
	v_add_f32_e32 v91, 1.0, v91
	v_add_f32_e32 v102, 1.0, v102
	v_add_f32_e32 v106, 1.0, v106
	v_add_f32_e32 v107, 1.0, v107
	v_rcp_f32_e32 v103, v103
	v_rcp_f32_e32 v104, v104
	v_rcp_f32_e32 v105, v105
	v_rcp_f32_e32 v108, v108
	v_rcp_f32_e32 v91, v91
	v_rcp_f32_e32 v102, v102
	v_rcp_f32_e32 v106, v106
	v_rcp_f32_e32 v107, v107
	v_mul_f32_e32 v85, v85, v103
	v_mul_f32_e32 v81, v81, v104
	v_mul_f32_e32 v89, v89, v105
	v_mul_f32_e32 v83, v83, v108
	v_mul_f32_e32 v91, v97, v91
	v_mul_f32_e32 v97, v99, v102
	v_mul_f32_e32 v93, v93, v106
	v_mul_f32_e32 v87, v87, v107
	v_mul_f32_e32 v84, v84, v85
	v_mul_f32_e32 v85, v80, v81
	v_mul_f32_e32 v81, v88, v89
	v_mul_f32_e32 v83, v82, v83
	v_mul_f32_e32 v91, v96, v91
	v_mul_f32_e32 v96, v98, v97
	v_mul_f32_e32 v88, v92, v93
	v_mul_f32_e32 v86, v86, v87
	v_cvt_pk_bf16_f32 v80, v91, v84
	v_cvt_pk_bf16_f32 v81, v81, v86
	v_cvt_pk_bf16_f32 v82, v96, v85
	v_cvt_pk_bf16_f32 v83, v88, v83
	global_store_dwordx4 v[94:95], v[80:83], off
	s_waitcnt vmcnt(7)
	s_nop 1
	v_mov_b32_e32 v84, v201
	s_nop 0
	v_mov_b32_e32 v81, v72
	v_mov_b32_e32 v72, v77
	v_mov_b32_e32 v77, v66
	v_mov_b32_e32 v80, v76
	v_mov_b32_e32 v76, v70
	v_mov_b32_e32 v82, v68
	v_mov_b32_e32 v68, v78
	v_mov_b32_e32 v83, v64
	v_mov_b32_e32 v64, v69
	v_mov_b32_e32 v69, v74
	v_mov_b32_e32 v74, v79
	v_fmamk_f32 v66, v84, 0x3a000000, v156
	s_nop 1
	v_rsq_f32_e32 v78, v66
	v_mov_b32_e32 v66, v71
	v_mad_i64_i32 v[70:71], s[4:5], v90, s43, v[146:147]
	v_lshl_add_u64 v[70:71], v[70:71], 0, v[120:121]
	s_nop 0
	s_nop 1
	s_nop 0
	v_mov_b32_e32 v78, v78
	s_nop 0
	v_mov_b32_e32 v78, v78
	v_pk_mul_f32 v[72:73], v[72:73], v[78:79] op_sel_hi:[1,0]
	v_pk_mul_f32 v[64:65], v[64:65], v[78:79] op_sel_hi:[1,0]
	v_pk_mul_f32 v[68:69], v[68:69], v[78:79] op_sel_hi:[1,0]
	v_pk_mul_f32 v[66:67], v[66:67], v[78:79] op_sel_hi:[1,0]
	v_pk_mul_f32 v[80:81], v[80:81], v[78:79] op_sel_hi:[1,0]
	v_pk_mul_f32 v[82:83], v[82:83], v[78:79] op_sel_hi:[1,0]
	v_pk_mul_f32 v[76:77], v[76:77], v[78:79] op_sel_hi:[1,0]
	v_pk_mul_f32 v[74:75], v[74:75], v[78:79] op_sel_hi:[1,0]
	v_mul_f32_e32 v84, 0xbfb8aa3b, v73
	v_mul_f32_e32 v85, 0xbfb8aa3b, v65
	v_mul_f32_e32 v86, 0xbfb8aa3b, v69
	v_mul_f32_e32 v89, 0xbfb8aa3b, v67
	v_mul_f32_e32 v78, 0xbfb8aa3b, v81
	v_mul_f32_e32 v79, 0xbfb8aa3b, v83
	v_mul_f32_e32 v87, 0xbfb8aa3b, v77
	v_mul_f32_e32 v88, 0xbfb8aa3b, v75
	v_exp_f32_e32 v84, v84
	v_exp_f32_e32 v85, v85
	v_exp_f32_e32 v86, v86
	v_exp_f32_e32 v89, v89
	v_exp_f32_e32 v78, v78
	v_exp_f32_e32 v79, v79
	v_exp_f32_e32 v87, v87
	v_exp_f32_e32 v88, v88
	v_add_f32_e32 v84, 1.0, v84
	v_add_f32_e32 v85, 1.0, v85
	v_add_f32_e32 v86, 1.0, v86
	v_add_f32_e32 v89, 1.0, v89
	v_add_f32_e32 v78, 1.0, v78
	v_add_f32_e32 v79, 1.0, v79
	v_add_f32_e32 v87, 1.0, v87
	v_add_f32_e32 v88, 1.0, v88
	v_rcp_f32_e32 v84, v84
	v_rcp_f32_e32 v85, v85
	v_rcp_f32_e32 v86, v86
	v_rcp_f32_e32 v89, v89
	v_rcp_f32_e32 v78, v78
	v_rcp_f32_e32 v79, v79
	v_rcp_f32_e32 v87, v87
	v_rcp_f32_e32 v88, v88
	v_mul_f32_e32 v73, v73, v84
	v_mul_f32_e32 v65, v65, v85
	v_mul_f32_e32 v69, v69, v86
	v_mul_f32_e32 v67, v67, v89
	v_mul_f32_e32 v78, v81, v78
	v_mul_f32_e32 v79, v83, v79
	v_mul_f32_e32 v77, v77, v87
	v_mul_f32_e32 v75, v75, v88
	v_mul_f32_e32 v72, v72, v73
	v_mul_f32_e32 v73, v64, v65
	v_mul_f32_e32 v65, v68, v69
	v_mul_f32_e32 v67, v66, v67
	v_mul_f32_e32 v78, v80, v78
	v_mul_f32_e32 v79, v82, v79
	v_mul_f32_e32 v68, v76, v77
	v_mul_f32_e32 v69, v74, v75
	v_cvt_pk_bf16_f32 v64, v78, v72
	v_cvt_pk_bf16_f32 v65, v65, v69
	v_cvt_pk_bf16_f32 v66, v79, v73
	v_cvt_pk_bf16_f32 v67, v68, v67
	global_store_dwordx4 v[70:71], v[64:67], off
	s_waitcnt vmcnt(7)
; __device__ __forceinline__ unsigned cvt_pk_bf16(float lo, float hi) { unsigned r; asm volatile("v_cvt_pk_bf16_f32 %0, %1, %2" : "=v"(r) : "v"(lo), "v"(hi)); return r; }
; __device__ __forceinline__ float silu_f(float g) { return g * __builtin_amdgcn_rcpf(1.0f + __builtin_amdgcn_exp2f(-1.44269504089f * g)); }
;     __device__ __forceinline__ void operator()(const f32x4 (&acc)[2][2][4][2], const Unit& u, int wr, int wc, int fr, int fq) const {
;     ...
;             for (int m = 0; m < 4; ++m) { bf16_t* rowp = O + (size_t)(row0 + ai * HALF + m * 16) * ldc + col0;
;                 const float rs = rowss ? 1.0f / sqrtf(rowss[row0 + ai * HALF + m * 16] * (1.0f / 2048.0f) + 1e-6f) : 1.0f;
;                 const f32x4 g0 = acc[ai][0][m][0] * rs, g1 = acc[ai][0][m][1] * rs, u0 = acc[ai][1][m][0] * rs, u1 = acc[ai][1][m][1] * rs;
;                 float h[8];
; #pragma unroll
;                 for (int j = 0; j < 4; ++j) { h[j] = silu_f(g0[j]) * u0[j]; h[4 + j] = silu_f(g1[j]) * u1[j]; }
;                 u32x4 w; w.x = cvt_pk_bf16(h[0], h[1]); w.y = cvt_pk_bf16(h[2], h[3]); w.z = cvt_pk_bf16(h[4], h[5]); w.w = cvt_pk_bf16(h[6], h[7]);
;                 *(u32x4*)rowp = w; }
	s_nop 1
	v_mov_b32_e32 v68, v202
	s_nop 0
	v_mov_b32_e32 v64, v60
	v_mov_b32_e32 v60, v58
	v_mov_b32_e32 v65, v52
	v_mov_b32_e32 v52, v61
	v_mov_b32_e32 v61, v50
	v_mov_b32_e32 v50, v59
	v_mov_b32_e32 v66, v56
	v_mov_b32_e32 v56, v62
	v_mov_b32_e32 v67, v48
	v_mov_b32_e32 v48, v57
	v_mov_b32_e32 v57, v54
	v_mov_b32_e32 v54, v63
	v_fmamk_f32 v58, v68, 0x3a000000, v156
	s_nop 1
	v_rsq_f32_e32 v62, v58
	v_add_u32_e32 v58, 0x80, v144
	v_mad_i64_i32 v[58:59], s[4:5], v58, s43, v[146:147]
	v_lshl_add_u64 v[58:59], v[58:59], 0, v[120:121]
	s_nop 0
	s_nop 1
	s_nop 0
	v_mov_b32_e32 v62, v62
	s_nop 0
	v_mov_b32_e32 v62, v62
	v_pk_mul_f32 v[52:53], v[52:53], v[62:63] op_sel_hi:[1,0]
	v_pk_mul_f32 v[48:49], v[48:49], v[62:63] op_sel_hi:[1,0]
	v_pk_mul_f32 v[56:57], v[56:57], v[62:63] op_sel_hi:[1,0]
	v_pk_mul_f32 v[50:51], v[50:51], v[62:63] op_sel_hi:[1,0]
	v_pk_mul_f32 v[64:65], v[64:65], v[62:63] op_sel_hi:[1,0]
	v_pk_mul_f32 v[66:67], v[66:67], v[62:63] op_sel_hi:[1,0]
	v_pk_mul_f32 v[60:61], v[60:61], v[62:63] op_sel_hi:[1,0]
	v_pk_mul_f32 v[54:55], v[54:55], v[62:63] op_sel_hi:[1,0]
	v_mul_f32_e32 v68, 0xbfb8aa3b, v53
	v_mul_f32_e32 v69, 0xbfb8aa3b, v49
	v_mul_f32_e32 v70, 0xbfb8aa3b, v57
	v_mul_f32_e32 v73, 0xbfb8aa3b, v51
	v_mul_f32_e32 v62, 0xbfb8aa3b, v65
	v_mul_f32_e32 v63, 0xbfb8aa3b, v67
	v_mul_f32_e32 v71, 0xbfb8aa3b, v61
	v_mul_f32_e32 v72, 0xbfb8aa3b, v55
	v_exp_f32_e32 v68, v68
	v_exp_f32_e32 v69, v69
	v_exp_f32_e32 v70, v70
	v_exp_f32_e32 v73, v73
	v_exp_f32_e32 v62, v62
	v_exp_f32_e32 v63, v63
	v_exp_f32_e32 v71, v71
	v_exp_f32_e32 v72, v72
	v_add_f32_e32 v68, 1.0, v68
	v_add_f32_e32 v69, 1.0, v69
	v_add_f32_e32 v70, 1.0, v70
	v_add_f32_e32 v73, 1.0, v73
	v_add_f32_e32 v62, 1.0, v62
	v_add_f32_e32 v63, 1.0, v63
	v_add_f32_e32 v71, 1.0, v71
	v_add_f32_e32 v72, 1.0, v72
	v_rcp_f32_e32 v68, v68
	v_rcp_f32_e32 v69, v69
	v_rcp_f32_e32 v70, v70
	v_rcp_f32_e32 v73, v73
	v_rcp_f32_e32 v62, v62
	v_rcp_f32_e32 v63, v63
	v_rcp_f32_e32 v71, v71
	v_rcp_f32_e32 v72, v72
	v_mul_f32_e32 v53, v53, v68
	v_mul_f32_e32 v49, v49, v69
	v_mul_f32_e32 v57, v57, v70
	v_mul_f32_e32 v51, v51, v73
	v_mul_f32_e32 v62, v65, v62
	v_mul_f32_e32 v63, v67, v63
	v_mul_f32_e32 v61, v61, v71
	v_mul_f32_e32 v55, v55, v72
	v_mul_f32_e32 v52, v52, v53
	v_mul_f32_e32 v53, v48, v49
	v_mul_f32_e32 v49, v56, v57
	v_mul_f32_e32 v51, v50, v51
	v_mul_f32_e32 v62, v64, v62
	v_mul_f32_e32 v63, v66, v63
	v_mul_f32_e32 v56, v60, v61
	v_mul_f32_e32 v54, v54, v55
	v_cvt_pk_bf16_f32 v48, v62, v52
	v_cvt_pk_bf16_f32 v49, v49, v54
	v_cvt_pk_bf16_f32 v50, v63, v53
	v_cvt_pk_bf16_f32 v51, v56, v51
	global_store_dwordx4 v[58:59], v[48:51], off
	s_waitcnt vmcnt(7)
	s_nop 1
	v_mov_b32_e32 v52, v203
	s_nop 0
	v_mov_b32_e32 v48, v44
	v_mov_b32_e32 v44, v42
	v_mov_b32_e32 v49, v36
	v_mov_b32_e32 v36, v45
	v_mov_b32_e32 v45, v34
	v_mov_b32_e32 v34, v43
	v_mov_b32_e32 v50, v40
	v_mov_b32_e32 v40, v46
	v_mov_b32_e32 v51, v32
	v_mov_b32_e32 v32, v41
	v_mov_b32_e32 v41, v38
	v_mov_b32_e32 v38, v47
	v_fmamk_f32 v42, v52, 0x3a000000, v156
	s_nop 1
	v_rsq_f32_e32 v46, v42
	v_add_u32_e32 v42, 0x90, v144
	v_mad_i64_i32 v[42:43], s[4:5], v42, s43, v[146:147]
	v_lshl_add_u64 v[42:43], v[42:43], 0, v[120:121]
	s_nop 0
	s_nop 1
	s_nop 0
	v_mov_b32_e32 v46, v46
	s_nop 0
	v_mov_b32_e32 v46, v46
	v_pk_mul_f32 v[36:37], v[36:37], v[46:47] op_sel_hi:[1,0]
	v_pk_mul_f32 v[32:33], v[32:33], v[46:47] op_sel_hi:[1,0]
	v_pk_mul_f32 v[40:41], v[40:41], v[46:47] op_sel_hi:[1,0]
	v_pk_mul_f32 v[34:35], v[34:35], v[46:47] op_sel_hi:[1,0]
	v_pk_mul_f32 v[48:49], v[48:49], v[46:47] op_sel_hi:[1,0]
	v_pk_mul_f32 v[50:51], v[50:51], v[46:47] op_sel_hi:[1,0]
	v_pk_mul_f32 v[44:45], v[44:45], v[46:47] op_sel_hi:[1,0]
	v_pk_mul_f32 v[38:39], v[38:39], v[46:47] op_sel_hi:[1,0]
	v_mul_f32_e32 v52, 0xbfb8aa3b, v37
	v_mul_f32_e32 v53, 0xbfb8aa3b, v33
	v_mul_f32_e32 v54, 0xbfb8aa3b, v41
	v_mul_f32_e32 v57, 0xbfb8aa3b, v35
	v_mul_f32_e32 v46, 0xbfb8aa3b, v49
	v_mul_f32_e32 v47, 0xbfb8aa3b, v51
	v_mul_f32_e32 v55, 0xbfb8aa3b, v45
	v_mul_f32_e32 v56, 0xbfb8aa3b, v39
	v_exp_f32_e32 v52, v52
	v_exp_f32_e32 v53, v53
	v_exp_f32_e32 v54, v54
	v_exp_f32_e32 v57, v57
	v_exp_f32_e32 v46, v46
	v_exp_f32_e32 v47, v47
	v_exp_f32_e32 v55, v55
	v_exp_f32_e32 v56, v56
	v_add_f32_e32 v52, 1.0, v52
	v_add_f32_e32 v53, 1.0, v53
	v_add_f32_e32 v54, 1.0, v54
	v_add_f32_e32 v57, 1.0, v57
	v_add_f32_e32 v46, 1.0, v46
	v_add_f32_e32 v47, 1.0, v47
	v_add_f32_e32 v55, 1.0, v55
	v_add_f32_e32 v56, 1.0, v56
	v_rcp_f32_e32 v52, v52
	v_rcp_f32_e32 v53, v53
	v_rcp_f32_e32 v54, v54
	v_rcp_f32_e32 v57, v57
	v_rcp_f32_e32 v46, v46
	v_rcp_f32_e32 v47, v47
	v_rcp_f32_e32 v55, v55
	v_rcp_f32_e32 v56, v56
	v_mul_f32_e32 v37, v37, v52
	v_mul_f32_e32 v33, v33, v53
	v_mul_f32_e32 v41, v41, v54
	v_mul_f32_e32 v35, v35, v57
	v_mul_f32_e32 v46, v49, v46
	v_mul_f32_e32 v47, v51, v47
	v_mul_f32_e32 v45, v45, v55
	v_mul_f32_e32 v39, v39, v56
	v_mul_f32_e32 v36, v36, v37
	v_mul_f32_e32 v37, v32, v33
	v_mul_f32_e32 v33, v40, v41
	v_mul_f32_e32 v35, v34, v35
	v_mul_f32_e32 v46, v48, v46
	v_mul_f32_e32 v47, v50, v47
	v_mul_f32_e32 v40, v44, v45
	v_mul_f32_e32 v38, v38, v39
	v_cvt_pk_bf16_f32 v32, v46, v36
	v_cvt_pk_bf16_f32 v33, v33, v38
	v_cvt_pk_bf16_f32 v34, v47, v37
	v_cvt_pk_bf16_f32 v35, v40, v35
	global_store_dwordx4 v[42:43], v[32:35], off
	s_waitcnt vmcnt(7)
; __device__ __forceinline__ unsigned cvt_pk_bf16(float lo, float hi) { unsigned r; asm volatile("v_cvt_pk_bf16_f32 %0, %1, %2" : "=v"(r) : "v"(lo), "v"(hi)); return r; }
; __device__ __forceinline__ float silu_f(float g) { return g * __builtin_amdgcn_rcpf(1.0f + __builtin_amdgcn_exp2f(-1.44269504089f * g)); }
;     __device__ __forceinline__ void operator()(const f32x4 (&acc)[2][2][4][2], const Unit& u, int wr, int wc, int fr, int fq) const {
;     ...
;             for (int m = 0; m < 4; ++m) { bf16_t* rowp = O + (size_t)(row0 + ai * HALF + m * 16) * ldc + col0;
;                 const float rs = rowss ? 1.0f / sqrtf(rowss[row0 + ai * HALF + m * 16] * (1.0f / 2048.0f) + 1e-6f) : 1.0f;
;                 const f32x4 g0 = acc[ai][0][m][0] * rs, g1 = acc[ai][0][m][1] * rs, u0 = acc[ai][1][m][0] * rs, u1 = acc[ai][1][m][1] * rs;
;                 float h[8];
; #pragma unroll
;                 for (int j = 0; j < 4; ++j) { h[j] = silu_f(g0[j]) * u0[j]; h[4 + j] = silu_f(g1[j]) * u1[j]; }
;                 u32x4 w; w.x = cvt_pk_bf16(h[0], h[1]); w.y = cvt_pk_bf16(h[2], h[3]); w.z = cvt_pk_bf16(h[4], h[5]); w.w = cvt_pk_bf16(h[6], h[7]);
;                 *(u32x4*)rowp = w; }
	s_nop 1
	v_mov_b32_e32 v36, v204
	s_nop 0
	v_mov_b32_e32 v32, v28
	v_mov_b32_e32 v28, v26
	v_mov_b32_e32 v33, v20
	v_mov_b32_e32 v20, v29
	v_mov_b32_e32 v29, v18
	v_mov_b32_e32 v18, v27
	v_mov_b32_e32 v34, v24
	v_mov_b32_e32 v24, v30
	v_mov_b32_e32 v35, v16
	v_mov_b32_e32 v16, v25
	v_mov_b32_e32 v25, v22
	v_mov_b32_e32 v22, v31
	v_fmamk_f32 v26, v36, 0x3a000000, v156
	s_nop 1
	v_rsq_f32_e32 v30, v26
	v_add_u32_e32 v26, 0xa0, v144
	v_mad_i64_i32 v[26:27], s[4:5], v26, s43, v[146:147]
	v_lshl_add_u64 v[26:27], v[26:27], 0, v[120:121]
	s_nop 0
	s_nop 1
	s_nop 0
	v_mov_b32_e32 v30, v30
	s_nop 0
	v_mov_b32_e32 v30, v30
	v_pk_mul_f32 v[20:21], v[20:21], v[30:31] op_sel_hi:[1,0]
	v_pk_mul_f32 v[16:17], v[16:17], v[30:31] op_sel_hi:[1,0]
	v_pk_mul_f32 v[24:25], v[24:25], v[30:31] op_sel_hi:[1,0]
	v_pk_mul_f32 v[18:19], v[18:19], v[30:31] op_sel_hi:[1,0]
	v_pk_mul_f32 v[32:33], v[32:33], v[30:31] op_sel_hi:[1,0]
	v_pk_mul_f32 v[34:35], v[34:35], v[30:31] op_sel_hi:[1,0]
	v_pk_mul_f32 v[28:29], v[28:29], v[30:31] op_sel_hi:[1,0]
	v_pk_mul_f32 v[22:23], v[22:23], v[30:31] op_sel_hi:[1,0]
	v_mul_f32_e32 v36, 0xbfb8aa3b, v21
	v_mul_f32_e32 v37, 0xbfb8aa3b, v17
	v_mul_f32_e32 v38, 0xbfb8aa3b, v25
	v_mul_f32_e32 v41, 0xbfb8aa3b, v19
	v_mul_f32_e32 v30, 0xbfb8aa3b, v33
	v_mul_f32_e32 v31, 0xbfb8aa3b, v35
	v_mul_f32_e32 v39, 0xbfb8aa3b, v29
	v_mul_f32_e32 v40, 0xbfb8aa3b, v23
	v_exp_f32_e32 v36, v36
	v_exp_f32_e32 v37, v37
	v_exp_f32_e32 v38, v38
	v_exp_f32_e32 v41, v41
	v_exp_f32_e32 v30, v30
	v_exp_f32_e32 v31, v31
	v_exp_f32_e32 v39, v39
	v_exp_f32_e32 v40, v40
	v_add_f32_e32 v36, 1.0, v36
	v_add_f32_e32 v37, 1.0, v37
	v_add_f32_e32 v38, 1.0, v38
	v_add_f32_e32 v41, 1.0, v41
	v_add_f32_e32 v30, 1.0, v30
	v_add_f32_e32 v31, 1.0, v31
	v_add_f32_e32 v39, 1.0, v39
	v_add_f32_e32 v40, 1.0, v40
	v_rcp_f32_e32 v36, v36
	v_rcp_f32_e32 v37, v37
	v_rcp_f32_e32 v38, v38
	v_rcp_f32_e32 v41, v41
	v_rcp_f32_e32 v30, v30
	v_rcp_f32_e32 v31, v31
	v_rcp_f32_e32 v39, v39
	v_rcp_f32_e32 v40, v40
	v_mul_f32_e32 v21, v21, v36
	v_mul_f32_e32 v17, v17, v37
	v_mul_f32_e32 v25, v25, v38
	v_mul_f32_e32 v19, v19, v41
	v_mul_f32_e32 v30, v33, v30
	v_mul_f32_e32 v31, v35, v31
	v_mul_f32_e32 v29, v29, v39
	v_mul_f32_e32 v23, v23, v40
	v_mul_f32_e32 v20, v20, v21
	v_mul_f32_e32 v21, v16, v17
	v_mul_f32_e32 v17, v24, v25
	v_mul_f32_e32 v19, v18, v19
	v_mul_f32_e32 v30, v32, v30
	v_mul_f32_e32 v31, v34, v31
	v_mul_f32_e32 v24, v28, v29
	v_mul_f32_e32 v22, v22, v23
	v_cvt_pk_bf16_f32 v16, v30, v20
	v_cvt_pk_bf16_f32 v17, v17, v22
	v_cvt_pk_bf16_f32 v18, v31, v21
	v_cvt_pk_bf16_f32 v19, v24, v19
	global_store_dwordx4 v[26:27], v[16:19], off
	s_waitcnt vmcnt(7)
	s_nop 1
	v_mov_b32_e32 v20, v205
	s_nop 0
	v_mov_b32_e32 v17, v4
	v_mov_b32_e32 v4, v13
	v_mov_b32_e32 v13, v2
	v_mov_b32_e32 v2, v11
	v_mov_b32_e32 v18, v8
	v_mov_b32_e32 v8, v14
	v_mov_b32_e32 v19, v0
	v_mov_b32_e32 v0, v9
	v_mov_b32_e32 v9, v6
	v_mov_b32_e32 v6, v15
	v_mov_b32_e32 v16, v12
	v_mov_b32_e32 v12, v10
	v_add_u32_e32 v10, 0xb0, v144
	v_fmamk_f32 v11, v20, 0x3a000000, v156
	s_nop 1
	v_rsq_f32_e32 v14, v11
	v_mad_i64_i32 v[10:11], s[4:5], v10, s43, v[146:147]
	v_lshl_add_u64 v[10:11], v[10:11], 0, v[120:121]
	s_nop 1
	s_nop 0
	v_mov_b32_e32 v14, v14
	s_mov_b64 s[4:5], -1
	s_nop 0
	v_mov_b32_e32 v14, v14
	v_pk_mul_f32 v[4:5], v[4:5], v[14:15] op_sel_hi:[1,0]
	v_pk_mul_f32 v[0:1], v[0:1], v[14:15] op_sel_hi:[1,0]
	v_pk_mul_f32 v[8:9], v[8:9], v[14:15] op_sel_hi:[1,0]
	v_pk_mul_f32 v[2:3], v[2:3], v[14:15] op_sel_hi:[1,0]
	v_pk_mul_f32 v[16:17], v[16:17], v[14:15] op_sel_hi:[1,0]
	v_pk_mul_f32 v[18:19], v[18:19], v[14:15] op_sel_hi:[1,0]
	v_pk_mul_f32 v[12:13], v[12:13], v[14:15] op_sel_hi:[1,0]
	v_pk_mul_f32 v[6:7], v[6:7], v[14:15] op_sel_hi:[1,0]
	v_mul_f32_e32 v20, 0xbfb8aa3b, v5
	v_mul_f32_e32 v21, 0xbfb8aa3b, v1
	v_mul_f32_e32 v22, 0xbfb8aa3b, v9
	v_mul_f32_e32 v25, 0xbfb8aa3b, v3
	v_mul_f32_e32 v14, 0xbfb8aa3b, v17
	v_mul_f32_e32 v15, 0xbfb8aa3b, v19
	v_mul_f32_e32 v23, 0xbfb8aa3b, v13
	v_mul_f32_e32 v24, 0xbfb8aa3b, v7
	v_exp_f32_e32 v20, v20
	v_exp_f32_e32 v21, v21
	v_exp_f32_e32 v22, v22
	v_exp_f32_e32 v25, v25
	v_exp_f32_e32 v14, v14
	v_exp_f32_e32 v15, v15
	v_exp_f32_e32 v23, v23
	v_exp_f32_e32 v24, v24
	v_add_f32_e32 v20, 1.0, v20
	v_add_f32_e32 v21, 1.0, v21
	v_add_f32_e32 v22, 1.0, v22
	v_add_f32_e32 v25, 1.0, v25
	v_add_f32_e32 v14, 1.0, v14
	v_add_f32_e32 v15, 1.0, v15
	v_add_f32_e32 v23, 1.0, v23
	v_add_f32_e32 v24, 1.0, v24
	v_rcp_f32_e32 v20, v20
	v_rcp_f32_e32 v21, v21
	v_rcp_f32_e32 v22, v22
	v_rcp_f32_e32 v25, v25
	v_rcp_f32_e32 v14, v14
	v_rcp_f32_e32 v15, v15
	v_rcp_f32_e32 v23, v23
	v_rcp_f32_e32 v24, v24
	v_mul_f32_e32 v5, v5, v20
	v_mul_f32_e32 v1, v1, v21
	v_mul_f32_e32 v9, v9, v22
	v_mul_f32_e32 v3, v3, v25
	s_andn2_b64 vcc, exec, s[6:7]
	v_mul_f32_e32 v14, v17, v14
	v_mul_f32_e32 v15, v19, v15
	v_mul_f32_e32 v13, v13, v23
	v_mul_f32_e32 v7, v7, v24
	v_mul_f32_e32 v4, v4, v5
	v_mul_f32_e32 v5, v0, v1
	v_mul_f32_e32 v1, v8, v9
	v_mul_f32_e32 v3, v2, v3
	v_mul_f32_e32 v14, v16, v14
	v_mul_f32_e32 v15, v18, v15
	v_mul_f32_e32 v8, v12, v13
	v_mul_f32_e32 v6, v6, v7
	v_cvt_pk_bf16_f32 v0, v14, v4
	v_cvt_pk_bf16_f32 v1, v1, v6
	v_cvt_pk_bf16_f32 v2, v15, v5
	v_cvt_pk_bf16_f32 v3, v8, v3
	global_store_dwordx4 v[10:11], v[0:3], off
	s_cbranch_vccnz .LBB0_925
	s_andn2_b64 vcc, exec, s[0:1]
	s_cbranch_vccnz .LBB0_924
	s_barrier
	s_branch .LBB0_924
